# row-sum butterflies in adaLN / post-pass / final norm: first four ds_bpermute steps replaced by DPP adds (quad_perm, row_half_mirror, row_mirror); on top of the attention LDS-read batching
# speedup vs baseline: 1.0055x; 1.0055x over previous
.LBB0_157:
	v_lshlrev_b32_e32 v85, 16, v22
	v_and_b32_e32 v87, 0xffff0000, v22
	v_and_b32_e32 v86, 0xffff0000, v20
	v_lshlrev_b32_e32 v89, 16, v23
	v_and_b32_e32 v23, 0xffff0000, v23
	v_and_b32_e32 v22, 0xffff0000, v21
	v_lshlrev_b32_e32 v84, 16, v20
	v_lshlrev_b32_e32 v88, 16, v21
	v_pk_mul_f32 v[20:21], v[86:87], v[86:87]
	v_pk_mul_f32 v[90:91], v[22:23], v[22:23]
	v_pk_fma_f32 v[20:21], v[84:85], v[84:85], v[20:21]
	v_pk_fma_f32 v[90:91], v[88:89], v[88:89], v[90:91]
	v_lshlrev_b32_e32 v97, 16, v17
	v_pk_add_f32 v[20:21], v[20:21], v[90:91]
	v_lshlrev_b32_e32 v96, 16, v16
	v_and_b32_e32 v17, 0xffff0000, v17
	v_and_b32_e32 v16, 0xffff0000, v16
	v_pk_add_f32 v[20:21], v[20:21], v[20:21] op_sel_hi:[0,1]
	v_lshlrev_b32_e32 v90, 16, v18
	v_and_b32_e32 v91, 0xffff0000, v18
	v_pk_mul_f32 v[98:99], v[16:17], v[16:17]
	v_lshlrev_b32_e32 v18, 16, v19
	v_lshlrev_b32_e32 v100, 16, v12
	v_pk_fma_f32 v[98:99], v[96:97], v[96:97], v[98:99]
	v_mul_f32_e32 v101, v90, v90
	v_mul_f32_e32 v103, v91, v91
	v_and_b32_e32 v19, 0xffff0000, v19
	v_mul_f32_e32 v20, v18, v18
	v_mov_b32_e32 v102, v100
	v_pk_add_f32 v[98:99], v[98:99], v[98:99] op_sel_hi:[0,1]
	v_pk_fma_f32 v[104:105], v[18:19], v[18:19], v[20:21] op_sel_hi:[1,1,0]
	v_and_b32_e32 v114, 0xffff0000, v12
	v_lshlrev_b32_e32 v12, 16, v13
	v_and_b32_e32 v13, 0xffff0000, v13
	v_pk_add_f32 v[102:103], v[100:101], v[102:103]
	v_mul_f32_e32 v104, v114, v114
	v_mul_f32_e32 v20, v12, v12
	v_mul_f32_e32 v98, v13, v13
	v_mul_f32_e32 v106, v100, v100
	v_mov_b32_e32 v107, v103
	v_pk_add_f32 v[102:103], v[106:107], v[104:105]
	v_pk_add_f32 v[20:21], v[20:21], v[98:99]
	v_lshlrev_b32_e32 v99, 16, v15
	v_lshlrev_b32_e32 v98, 16, v14
	v_and_b32_e32 v15, 0xffff0000, v15
	v_and_b32_e32 v14, 0xffff0000, v14
	v_pk_add_f32 v[20:21], v[102:103], v[20:21]
	v_pk_mul_f32 v[102:103], v[14:15], v[14:15]
	v_lshlrev_b32_e32 v104, 16, v8
	v_and_b32_e32 v105, 0xffff0000, v8
	v_lshlrev_b32_e32 v106, 16, v10
	v_lshlrev_b32_e32 v110, 16, v9
	v_pk_fma_f32 v[102:103], v[98:99], v[98:99], v[102:103]
	v_and_b32_e32 v115, 0xffff0000, v10
	v_lshlrev_b32_e32 v108, 16, v11
	v_and_b32_e32 v109, 0xffff0000, v11
	v_mul_f32_e32 v107, v104, v104
	v_mul_f32_e32 v11, v105, v105
	v_and_b32_e32 v111, 0xffff0000, v9
	v_mul_f32_e32 v8, v110, v110
	v_mov_b32_e32 v10, v106
	v_pk_add_f32 v[20:21], v[20:21], v[20:21] op_sel_hi:[0,1]
	v_pk_add_f32 v[102:103], v[102:103], v[102:103] op_sel_hi:[0,1]
	v_pk_fma_f32 v[8:9], v[110:111], v[110:111], v[8:9] op_sel_hi:[1,1,0]
	v_pk_add_f32 v[10:11], v[106:107], v[10:11]
	v_mul_f32_e32 v8, v115, v115
	v_mul_f32_e32 v102, v108, v108
	v_mul_f32_e32 v20, v109, v109
	v_mul_f32_e32 v112, v106, v106
	v_mov_b32_e32 v113, v11
	v_pk_add_f32 v[8:9], v[112:113], v[8:9]
	v_pk_add_f32 v[10:11], v[102:103], v[20:21]
	s_ashr_i32 s17, s16, 31
	v_pk_add_f32 v[8:9], v[8:9], v[10:11]
	v_mov_b32_e32 v101, v114
	v_add_f32_e32 v8, v8, v9
	ds_bpermute_b32 v9, v1, v8
	v_mov_b32_e32 v107, v115
	s_waitcnt lgkmcnt(0)
	v_add_f32_e32 v8, v8, v9
	s_nop 1
	v_add_f32_dpp v8, v8, v8 quad_perm:[2,3,0,1] row_mask:0xf bank_mask:0xf
	s_nop 1
	v_add_f32_dpp v8, v8, v8 row_half_mirror row_mask:0xf bank_mask:0xf
	s_nop 1
	v_add_f32_dpp v8, v8, v8 row_mirror row_mask:0xf bank_mask:0xf
	ds_bpermute_b32 v9, v131, v8
	s_waitcnt lgkmcnt(0)
	v_add_f32_e32 v8, v8, v9
	ds_bpermute_b32 v9, v134, v8
	s_waitcnt lgkmcnt(0)
	v_add_f32_e32 v8, v8, v9
	v_fmamk_f32 v8, v8, 0x3a000000, v234
	v_mul_f32_e32 v9, 0x4f800000, v8
	v_cmp_gt_f32_e32 vcc, s3, v8
	s_nop 1
	v_cndmask_b32_e32 v8, v8, v9, vcc
	v_sqrt_f32_e32 v9, v8
	s_nop 0
	v_add_u32_e32 v10, -1, v9
	v_fma_f32 v11, -v10, v9, v8
	v_cmp_ge_f32_e64 s[48:49], 0, v11
	v_add_u32_e32 v11, 1, v9
	s_nop 0
	v_cndmask_b32_e64 v10, v9, v10, s[48:49]
	v_fma_f32 v9, -v11, v9, v8
	v_cmp_lt_f32_e64 s[48:49], 0, v9
	s_nop 1
	v_cndmask_b32_e64 v9, v10, v11, s[48:49]
	v_mul_f32_e32 v10, 0x37800000, v9
	v_cndmask_b32_e32 v9, v9, v10, vcc
	v_cmp_class_f32_e32 vcc, v8, v235
	s_nop 1
	v_cndmask_b32_e32 v8, v9, v8, vcc
	v_div_scale_f32 v9, s[12:13], v8, v8, 1.0
	v_rcp_f32_e32 v10, v9
	s_lshl_b64 s[12:13], s[16:17], 12
	v_lshl_add_u64 v[102:103], v[122:123], 0, s[12:13]
	v_fma_f32 v11, -v9, v10, 1.0
	v_fmac_f32_e32 v10, v11, v10
	v_div_scale_f32 v11, vcc, 1.0, v8, 1.0
	v_mul_f32_e32 v20, v11, v10
	v_fma_f32 v21, -v9, v20, v11
	v_fmac_f32_e32 v20, v21, v10
	v_fma_f32 v9, -v9, v20, v11
	v_div_fmas_f32 v9, v9, v10, v20
	v_div_fixup_f32 v20, v9, v8, 1.0
	v_mov_b32_e32 v8, v84
	v_mov_b32_e32 v9, v86
	v_mov_b32_e32 v10, v88
	v_mov_b32_e32 v11, v22
	v_mov_b32_e32 v86, v85
	v_mov_b32_e32 v22, v89
	v_pk_mul_f32 v[8:9], v[20:21], v[8:9] op_sel_hi:[0,1]
	v_pk_mul_f32 v[10:11], v[20:21], v[10:11] op_sel_hi:[0,1]
	v_pk_mul_f32 v[84:85], v[20:21], v[86:87] op_sel_hi:[0,1]
	v_pk_mul_f32 v[22:23], v[20:21], v[22:23] op_sel_hi:[0,1]
	s_waitcnt vmcnt(6)
	v_pk_fma_f32 v[10:11], v[46:47], v[10:11], v[30:31]
	v_pk_fma_f32 v[8:9], v[44:45], v[8:9], v[28:29]
	v_pk_fma_f32 v[22:23], v[54:55], v[22:23], v[26:27]
	v_pk_fma_f32 v[84:85], v[52:53], v[84:85], v[24:25]
	v_cvt_pk_bf16_f32 v8, v8, v9
	v_cvt_pk_bf16_f32 v9, v10, v11
	v_cvt_pk_bf16_f32 v10, v84, v85
	v_cvt_pk_bf16_f32 v11, v22, v23
	global_store_dwordx4 v[102:103], v[8:11], off
	v_pk_mul_f32 v[18:19], v[20:21], v[18:19] op_sel_hi:[0,1]
	s_waitcnt vmcnt(6)
	v_pk_fma_f32 v[18:19], v[62:63], v[18:19], v[34:35]
	v_mov_b32_e32 v8, v96
	v_mov_b32_e32 v9, v16
	v_mov_b32_e32 v16, v97
	v_pk_mul_f32 v[8:9], v[20:21], v[8:9] op_sel_hi:[0,1]
	v_pk_mul_f32 v[10:11], v[20:21], v[16:17] op_sel_hi:[0,1]
	v_pk_mul_f32 v[16:17], v[20:21], v[90:91] op_sel_hi:[0,1]
	s_waitcnt vmcnt(5)
	v_pk_fma_f32 v[10:11], v[58:59], v[10:11], v[38:39]
	v_pk_fma_f32 v[8:9], v[56:57], v[8:9], v[36:37]
	v_pk_fma_f32 v[16:17], v[60:61], v[16:17], v[32:33]
	v_cvt_pk_bf16_f32 v8, v8, v9
	v_cvt_pk_bf16_f32 v9, v10, v11
	v_cvt_pk_bf16_f32 v10, v16, v17
	v_cvt_pk_bf16_f32 v11, v18, v19
	global_store_dwordx4 v[102:103], v[8:11], off offset:1024
	s_nop 1
	v_pk_mul_f32 v[10:11], v[20:21], v[12:13] op_sel_hi:[0,1]
	v_mov_b32_e32 v12, v98
	v_mov_b32_e32 v13, v14
	v_mov_b32_e32 v14, v99
	v_pk_mul_f32 v[8:9], v[20:21], v[100:101] op_sel_hi:[0,1]
	v_pk_mul_f32 v[12:13], v[20:21], v[12:13] op_sel_hi:[0,1]
	v_pk_mul_f32 v[14:15], v[20:21], v[14:15] op_sel_hi:[0,1]
	s_waitcnt vmcnt(4)
	v_pk_fma_f32 v[10:11], v[66:67], v[10:11], v[50:51]
	v_pk_fma_f32 v[8:9], v[64:65], v[8:9], v[48:49]
	v_pk_fma_f32 v[14:15], v[70:71], v[14:15], v[42:43]
	v_pk_fma_f32 v[12:13], v[68:69], v[12:13], v[40:41]
	v_cvt_pk_bf16_f32 v8, v8, v9
	v_cvt_pk_bf16_f32 v9, v10, v11
	v_cvt_pk_bf16_f32 v10, v12, v13
	v_cvt_pk_bf16_f32 v11, v14, v15
	global_store_dwordx4 v[102:103], v[8:11], off offset:2048
	v_pk_mul_f32 v[12:13], v[20:21], v[106:107] op_sel_hi:[0,1]
	v_pk_mul_f32 v[14:15], v[20:21], v[108:109] op_sel_hi:[0,1]
	v_pk_mul_f32 v[8:9], v[20:21], v[104:105] op_sel_hi:[0,1]
	v_pk_mul_f32 v[10:11], v[20:21], v[110:111] op_sel_hi:[0,1]
	s_waitcnt vmcnt(3)
	v_pk_fma_f32 v[10:11], v[82:83], v[10:11], v[78:79]
	v_pk_fma_f32 v[8:9], v[80:81], v[8:9], v[76:77]
	v_pk_fma_f32 v[14:15], v[94:95], v[14:15], v[74:75]
	v_pk_fma_f32 v[12:13], v[92:93], v[12:13], v[72:73]
	v_cvt_pk_bf16_f32 v8, v8, v9
	v_cvt_pk_bf16_f32 v9, v10, v11
	v_cvt_pk_bf16_f32 v10, v12, v13
	v_cvt_pk_bf16_f32 v11, v14, v15
	global_store_dwordx4 v[102:103], v[8:11], off offset:3072

.LBB0_161:
	s_waitcnt vmcnt(0)
	v_lshlrev_b32_e32 v137, 16, v118
	v_and_b32_e32 v139, 0xffff0000, v118
	v_and_b32_e32 v138, 0xffff0000, v116
	v_lshlrev_b32_e32 v141, 16, v119
	v_and_b32_e32 v119, 0xffff0000, v119
	v_and_b32_e32 v118, 0xffff0000, v117
	v_lshlrev_b32_e32 v136, 16, v116
	v_lshlrev_b32_e32 v140, 16, v117
	v_pk_mul_f32 v[116:117], v[138:139], v[138:139]
	v_pk_mul_f32 v[142:143], v[118:119], v[118:119]
	v_pk_fma_f32 v[116:117], v[136:137], v[136:137], v[116:117]
	v_pk_fma_f32 v[142:143], v[140:141], v[140:141], v[142:143]
	s_waitcnt vmcnt(10)
	v_lshlrev_b32_e32 v145, 16, v113
	v_pk_add_f32 v[116:117], v[116:117], v[142:143]
	v_lshlrev_b32_e32 v144, 16, v112
	v_and_b32_e32 v113, 0xffff0000, v113
	v_and_b32_e32 v112, 0xffff0000, v112
	v_pk_add_f32 v[116:117], v[116:117], v[116:117] op_sel_hi:[0,1]
	v_lshlrev_b32_e32 v142, 16, v114
	v_and_b32_e32 v143, 0xffff0000, v114
	v_pk_mul_f32 v[146:147], v[112:113], v[112:113]
	v_lshlrev_b32_e32 v114, 16, v115
	s_waitcnt vmcnt(9)
	v_lshlrev_b32_e32 v148, 16, v108
	v_pk_fma_f32 v[146:147], v[144:145], v[144:145], v[146:147]
	v_mul_f32_e32 v149, v142, v142
	v_mul_f32_e32 v151, v143, v143
	v_and_b32_e32 v115, 0xffff0000, v115
	v_mul_f32_e32 v116, v114, v114
	v_mov_b32_e32 v150, v148
	v_pk_add_f32 v[146:147], v[146:147], v[146:147] op_sel_hi:[0,1]
	v_pk_fma_f32 v[152:153], v[114:115], v[114:115], v[116:117] op_sel_hi:[1,1,0]
	v_and_b32_e32 v135, 0xffff0000, v108
	v_lshlrev_b32_e32 v108, 16, v109
	v_and_b32_e32 v109, 0xffff0000, v109
	v_pk_add_f32 v[150:151], v[148:149], v[150:151]
	v_mul_f32_e32 v152, v135, v135
	v_mul_f32_e32 v116, v108, v108
	v_mul_f32_e32 v146, v109, v109
	v_mul_f32_e32 v154, v148, v148
	v_mov_b32_e32 v155, v151
	v_pk_add_f32 v[150:151], v[154:155], v[152:153]
	v_pk_add_f32 v[116:117], v[116:117], v[146:147]
	v_lshlrev_b32_e32 v147, 16, v111
	v_lshlrev_b32_e32 v146, 16, v110
	v_and_b32_e32 v111, 0xffff0000, v111
	v_and_b32_e32 v110, 0xffff0000, v110
	v_pk_add_f32 v[116:117], v[150:151], v[116:117]
	v_pk_mul_f32 v[150:151], v[110:111], v[110:111]
	s_waitcnt vmcnt(8)
	v_lshlrev_b32_e32 v152, 16, v104
	v_and_b32_e32 v153, 0xffff0000, v104
	v_lshlrev_b32_e32 v154, 16, v106
	v_lshlrev_b32_e32 v158, 16, v105
	v_pk_fma_f32 v[150:151], v[146:147], v[146:147], v[150:151]
	v_and_b32_e32 v162, 0xffff0000, v106
	v_lshlrev_b32_e32 v156, 16, v107
	v_and_b32_e32 v157, 0xffff0000, v107
	v_mul_f32_e32 v155, v152, v152
	v_mul_f32_e32 v107, v153, v153
	v_and_b32_e32 v159, 0xffff0000, v105
	v_mul_f32_e32 v104, v158, v158
	v_mov_b32_e32 v106, v154
	v_pk_add_f32 v[116:117], v[116:117], v[116:117] op_sel_hi:[0,1]
	v_pk_add_f32 v[150:151], v[150:151], v[150:151] op_sel_hi:[0,1]
	v_pk_fma_f32 v[104:105], v[158:159], v[158:159], v[104:105] op_sel_hi:[1,1,0]
	v_pk_add_f32 v[106:107], v[154:155], v[106:107]
	v_mul_f32_e32 v104, v162, v162
	v_mul_f32_e32 v150, v156, v156
	v_mul_f32_e32 v116, v157, v157
	v_mul_f32_e32 v160, v154, v154
	v_mov_b32_e32 v161, v107
	v_pk_add_f32 v[104:105], v[160:161], v[104:105]
	v_pk_add_f32 v[106:107], v[150:151], v[116:117]
	v_lshl_add_u64 v[150:151], s[10:11], 0, v[2:3]
	v_pk_add_f32 v[104:105], v[104:105], v[106:107]
	v_mov_b32_e32 v149, v135
	v_add_f32_e32 v104, v104, v105
	v_mov_b32_e32 v155, v162
	s_cmp_ge_i32 s9, s14
	s_nop 1
	v_add_f32_dpp v104, v104, v104 quad_perm:[1,0,3,2] row_mask:0xf bank_mask:0xf
	s_nop 1
	v_add_f32_dpp v104, v104, v104 quad_perm:[2,3,0,1] row_mask:0xf bank_mask:0xf
	s_nop 1
	v_add_f32_dpp v104, v104, v104 row_half_mirror row_mask:0xf bank_mask:0xf
	s_nop 1
	v_add_f32_dpp v104, v104, v104 row_mirror row_mask:0xf bank_mask:0xf
	ds_bpermute_b32 v105, v131, v104
	s_waitcnt lgkmcnt(0)
	v_add_f32_e32 v104, v104, v105
	ds_bpermute_b32 v105, v134, v104
	s_waitcnt lgkmcnt(0)
	v_add_f32_e32 v104, v104, v105
	v_fmamk_f32 v104, v104, 0x3a000000, v234
	v_mul_f32_e32 v105, 0x4f800000, v104
	v_cmp_gt_f32_e32 vcc, s3, v104
	s_nop 1
	v_cndmask_b32_e32 v104, v104, v105, vcc
	v_sqrt_f32_e32 v105, v104
	s_nop 0
	v_add_u32_e32 v106, -1, v105
	v_fma_f32 v107, -v106, v105, v104
	v_cmp_ge_f32_e64 s[48:49], 0, v107
	v_add_u32_e32 v107, 1, v105
	s_nop 0
	v_cndmask_b32_e64 v106, v105, v106, s[48:49]
	v_fma_f32 v105, -v107, v105, v104
	v_cmp_lt_f32_e64 s[48:49], 0, v105
	s_nop 1
	v_cndmask_b32_e64 v105, v106, v107, s[48:49]
	v_mul_f32_e32 v106, 0x37800000, v105
	v_cndmask_b32_e32 v105, v105, v106, vcc
	v_cmp_class_f32_e32 vcc, v104, v235
	s_nop 1
	v_cndmask_b32_e32 v104, v105, v104, vcc
	v_div_scale_f32 v105, s[12:13], v104, v104, 1.0
	v_rcp_f32_e32 v106, v105
	s_nop 0
	v_fma_f32 v107, -v105, v106, 1.0
	v_fmac_f32_e32 v106, v107, v106
	v_div_scale_f32 v107, vcc, 1.0, v104, 1.0
	v_mul_f32_e32 v116, v107, v106
	v_fma_f32 v117, -v105, v116, v107
	v_fmac_f32_e32 v116, v117, v106
	v_fma_f32 v105, -v105, v116, v107
	v_div_fmas_f32 v105, v105, v106, v116
	v_div_fixup_f32 v116, v105, v104, 1.0
	v_mov_b32_e32 v104, v136
	v_mov_b32_e32 v105, v138
	v_mov_b32_e32 v106, v140
	v_mov_b32_e32 v107, v118
	v_mov_b32_e32 v118, v141
	v_pk_mul_f32 v[104:105], v[116:117], v[104:105] op_sel_hi:[0,1]
	v_pk_mul_f32 v[106:107], v[116:117], v[106:107] op_sel_hi:[0,1]
	v_mov_b32_e32 v138, v137
	v_pk_mul_f32 v[118:119], v[116:117], v[118:119] op_sel_hi:[0,1]
	s_waitcnt vmcnt(6)
	v_pk_fma_f32 v[106:107], v[46:47], v[106:107], v[30:31]
	v_pk_fma_f32 v[104:105], v[44:45], v[104:105], v[28:29]
	v_pk_mul_f32 v[136:137], v[116:117], v[138:139] op_sel_hi:[0,1]
	v_pk_fma_f32 v[118:119], v[54:55], v[118:119], v[26:27]
	v_pk_fma_f32 v[136:137], v[52:53], v[136:137], v[24:25]
	v_cvt_pk_bf16_f32 v104, v104, v105
	v_cvt_pk_bf16_f32 v105, v106, v107
	v_cvt_pk_bf16_f32 v107, v118, v119
	v_add_co_u32_e32 v118, vcc, s24, v150
	v_cvt_pk_bf16_f32 v106, v136, v137
	s_nop 0
	v_addc_co_u32_e32 v119, vcc, 0, v151, vcc
	global_store_dwordx4 v[118:119], v[104:107], off
	v_pk_mul_f32 v[114:115], v[116:117], v[114:115] op_sel_hi:[0,1]
	s_waitcnt vmcnt(6)
	v_pk_fma_f32 v[114:115], v[62:63], v[114:115], v[34:35]
	v_mov_b32_e32 v104, v144
	v_mov_b32_e32 v105, v112
	v_mov_b32_e32 v112, v145
	v_pk_mul_f32 v[104:105], v[116:117], v[104:105] op_sel_hi:[0,1]
	v_pk_mul_f32 v[106:107], v[116:117], v[112:113] op_sel_hi:[0,1]
	v_pk_mul_f32 v[112:113], v[116:117], v[142:143] op_sel_hi:[0,1]
	s_waitcnt vmcnt(5)
	v_pk_fma_f32 v[106:107], v[58:59], v[106:107], v[38:39]
	v_pk_fma_f32 v[104:105], v[56:57], v[104:105], v[36:37]
	v_pk_fma_f32 v[112:113], v[60:61], v[112:113], v[32:33]
	v_cvt_pk_bf16_f32 v104, v104, v105
	v_cvt_pk_bf16_f32 v105, v106, v107
	v_cvt_pk_bf16_f32 v106, v112, v113
	v_cvt_pk_bf16_f32 v107, v114, v115
	global_store_dwordx4 v[118:119], v[104:107], off offset:1024
	s_nop 1
	v_pk_mul_f32 v[106:107], v[116:117], v[108:109] op_sel_hi:[0,1]
	v_mov_b32_e32 v108, v146
	v_mov_b32_e32 v109, v110
	v_mov_b32_e32 v110, v147
	v_pk_mul_f32 v[104:105], v[116:117], v[148:149] op_sel_hi:[0,1]
	v_pk_mul_f32 v[108:109], v[116:117], v[108:109] op_sel_hi:[0,1]
	v_pk_mul_f32 v[110:111], v[116:117], v[110:111] op_sel_hi:[0,1]
	s_waitcnt vmcnt(4)
	v_pk_fma_f32 v[106:107], v[66:67], v[106:107], v[50:51]
	v_pk_fma_f32 v[104:105], v[64:65], v[104:105], v[48:49]
	v_pk_fma_f32 v[110:111], v[70:71], v[110:111], v[42:43]
	v_pk_fma_f32 v[108:109], v[68:69], v[108:109], v[40:41]
	v_cvt_pk_bf16_f32 v104, v104, v105
	v_cvt_pk_bf16_f32 v105, v106, v107
	v_cvt_pk_bf16_f32 v106, v108, v109
	v_cvt_pk_bf16_f32 v107, v110, v111
	global_store_dwordx4 v[118:119], v[104:107], off offset:2048
	v_pk_mul_f32 v[108:109], v[116:117], v[154:155] op_sel_hi:[0,1]
	v_pk_mul_f32 v[110:111], v[116:117], v[156:157] op_sel_hi:[0,1]
	v_pk_mul_f32 v[104:105], v[116:117], v[152:153] op_sel_hi:[0,1]
	v_pk_mul_f32 v[106:107], v[116:117], v[158:159] op_sel_hi:[0,1]
	s_waitcnt vmcnt(3)
	v_pk_fma_f32 v[106:107], v[82:83], v[106:107], v[78:79]
	v_pk_fma_f32 v[104:105], v[80:81], v[104:105], v[76:77]
	v_pk_fma_f32 v[110:111], v[94:95], v[110:111], v[74:75]
	v_pk_fma_f32 v[108:109], v[92:93], v[108:109], v[72:73]
	v_cvt_pk_bf16_f32 v104, v104, v105
	v_cvt_pk_bf16_f32 v105, v106, v107
	v_cvt_pk_bf16_f32 v106, v108, v109
	v_cvt_pk_bf16_f32 v107, v110, v111
	global_store_dwordx4 v[118:119], v[104:107], off offset:3072
	s_cbranch_scc1 .LBB0_165
	s_add_i32 s9, s8, 0xfffff001
	s_lshr_b32 s9, s9, 10
	s_add_i32 s9, s9, 1
	s_cmpk_gt_i32 s8, 0xffe
	s_cselect_b32 s9, s9, 0
	s_cmp_eq_u32 s9, s20
	s_cbranch_scc1 .LBB0_164
	s_mul_i32 s13, s9, 0x12000
	s_mul_hi_u32 s12, s9, 0x12000
	s_add_u32 s17, s15, s13
	s_addc_u32 s22, s18, s12
	s_lshl_b64 s[12:13], s[42:43], 2
	s_add_u32 s12, s17, s12
	s_addc_u32 s13, s22, s13
	v_lshlrev_b32_e32 v60, 2, v120
	global_load_dwordx4 v[32:35], v[124:125], off offset:16
	global_load_dwordx4 v[24:27], v[124:125], off
	global_load_dwordx4 v[36:39], v60, s[12:13] offset:16
	global_load_dwordx4 v[28:31], v60, s[12:13]
	s_lshl_b64 s[20:21], s[36:37], 2
	s_add_u32 s20, s17, s20
	s_addc_u32 s21, s22, s21
	v_lshlrev_b32_e32 v76, 2, v126
	v_lshlrev_b32_e32 v108, 2, v130
	s_waitcnt vmcnt(1)
	v_pk_add_f32 v[38:39], v[38:39], 1.0 op_sel_hi:[1,0]
	s_waitcnt vmcnt(0)
	v_pk_add_f32 v[30:31], v[30:31], 1.0 op_sel_hi:[1,0]
	v_pk_add_f32 v[28:29], v[28:29], 1.0 op_sel_hi:[1,0]
	v_pk_add_f32 v[36:37], v[36:37], 1.0 op_sel_hi:[1,0]
	v_pk_mul_f32 v[46:47], v[26:27], v[30:31]
	v_pk_mul_f32 v[44:45], v[24:25], v[28:29]
	global_load_dwordx4 v[24:27], v60, s[20:21] offset:16
	global_load_dwordx4 v[28:31], v60, s[20:21]
	v_pk_mul_f32 v[54:55], v[34:35], v[38:39]
	v_pk_mul_f32 v[52:53], v[32:33], v[36:37]
	global_load_dwordx4 v[40:43], v[124:125], off offset:2064
	global_load_dwordx4 v[32:35], v[124:125], off offset:2048
	global_load_dwordx4 v[48:51], v60, s[12:13] offset:2064
	global_load_dwordx4 v[36:39], v60, s[12:13] offset:2048
	s_waitcnt vmcnt(1)
	v_pk_add_f32 v[50:51], v[50:51], 1.0 op_sel_hi:[1,0]
	s_waitcnt vmcnt(0)
	v_pk_add_f32 v[38:39], v[38:39], 1.0 op_sel_hi:[1,0]
	v_pk_add_f32 v[36:37], v[36:37], 1.0 op_sel_hi:[1,0]
	v_pk_add_f32 v[48:49], v[48:49], 1.0 op_sel_hi:[1,0]
	v_pk_mul_f32 v[58:59], v[34:35], v[38:39]
	v_pk_mul_f32 v[56:57], v[32:33], v[36:37]
	global_load_dwordx4 v[32:35], v60, s[20:21] offset:2064
	global_load_dwordx4 v[36:39], v60, s[20:21] offset:2048
	v_pk_mul_f32 v[62:63], v[42:43], v[50:51]
	v_pk_mul_f32 v[60:61], v[40:41], v[48:49]
	global_load_dwordx4 v[68:71], v[128:129], off offset:16
	global_load_dwordx4 v[40:43], v[128:129], off
	global_load_dwordx4 v[72:75], v76, s[12:13] offset:16
	global_load_dwordx4 v[48:51], v76, s[12:13]
	s_waitcnt vmcnt(1)
	v_pk_add_f32 v[74:75], v[74:75], 1.0 op_sel_hi:[1,0]
	s_waitcnt vmcnt(0)
	v_pk_add_f32 v[50:51], v[50:51], 1.0 op_sel_hi:[1,0]
	v_pk_add_f32 v[48:49], v[48:49], 1.0 op_sel_hi:[1,0]
	v_pk_add_f32 v[72:73], v[72:73], 1.0 op_sel_hi:[1,0]
	v_pk_mul_f32 v[66:67], v[42:43], v[50:51]
	v_pk_mul_f32 v[64:65], v[40:41], v[48:49]
	global_load_dwordx4 v[40:43], v76, s[20:21] offset:16
	global_load_dwordx4 v[48:51], v76, s[20:21]
	v_pk_mul_f32 v[70:71], v[70:71], v[74:75]
	v_pk_mul_f32 v[68:69], v[68:69], v[72:73]
	global_load_dwordx4 v[92:95], v[132:133], off offset:16
	global_load_dwordx4 v[72:75], v[132:133], off
	global_load_dwordx4 v[104:107], v108, s[12:13] offset:16
	global_load_dwordx4 v[76:79], v108, s[12:13]
	s_waitcnt vmcnt(1)
	v_pk_add_f32 v[106:107], v[106:107], 1.0 op_sel_hi:[1,0]
	s_waitcnt vmcnt(0)
	v_pk_add_f32 v[78:79], v[78:79], 1.0 op_sel_hi:[1,0]
	v_pk_add_f32 v[76:77], v[76:77], 1.0 op_sel_hi:[1,0]
	v_pk_mul_f32 v[82:83], v[74:75], v[78:79]
	v_pk_mul_f32 v[80:81], v[72:73], v[76:77]
	global_load_dwordx4 v[72:75], v108, s[20:21] offset:16
	global_load_dwordx4 v[76:79], v108, s[20:21]
	v_pk_add_f32 v[104:105], v[104:105], 1.0 op_sel_hi:[1,0]
	v_pk_mul_f32 v[94:95], v[94:95], v[106:107]
	v_pk_mul_f32 v[92:93], v[92:93], v[104:105]
	s_mov_b32 s20, s9
.LBB0_164:
	v_lshlrev_b32_e32 v105, 16, v102
	v_and_b32_e32 v107, 0xffff0000, v102
	v_and_b32_e32 v106, 0xffff0000, v100
	v_lshlrev_b32_e32 v109, 16, v103
	v_and_b32_e32 v103, 0xffff0000, v103
	v_and_b32_e32 v102, 0xffff0000, v101
	v_lshlrev_b32_e32 v104, 16, v100
	v_lshlrev_b32_e32 v108, 16, v101
	v_pk_mul_f32 v[100:101], v[106:107], v[106:107]
	v_pk_mul_f32 v[110:111], v[102:103], v[102:103]
	v_pk_fma_f32 v[100:101], v[104:105], v[104:105], v[100:101]
	v_pk_fma_f32 v[110:111], v[108:109], v[108:109], v[110:111]
	v_lshlrev_b32_e32 v113, 16, v97
	v_pk_add_f32 v[100:101], v[100:101], v[110:111]
	v_lshlrev_b32_e32 v112, 16, v96
	v_and_b32_e32 v97, 0xffff0000, v97
	v_and_b32_e32 v96, 0xffff0000, v96
	v_pk_add_f32 v[100:101], v[100:101], v[100:101] op_sel_hi:[0,1]
	v_lshlrev_b32_e32 v110, 16, v98
	v_and_b32_e32 v111, 0xffff0000, v98
	v_pk_mul_f32 v[114:115], v[96:97], v[96:97]
	v_lshlrev_b32_e32 v98, 16, v99
	v_lshlrev_b32_e32 v116, 16, v88
	v_pk_fma_f32 v[114:115], v[112:113], v[112:113], v[114:115]
	v_mul_f32_e32 v117, v110, v110
	v_mul_f32_e32 v119, v111, v111
	v_and_b32_e32 v99, 0xffff0000, v99
	v_mul_f32_e32 v100, v98, v98
	v_mov_b32_e32 v118, v116
	v_pk_add_f32 v[114:115], v[114:115], v[114:115] op_sel_hi:[0,1]
	v_pk_fma_f32 v[136:137], v[98:99], v[98:99], v[100:101] op_sel_hi:[1,1,0]
	v_and_b32_e32 v135, 0xffff0000, v88
	v_lshlrev_b32_e32 v88, 16, v89
	v_and_b32_e32 v89, 0xffff0000, v89
	v_pk_add_f32 v[118:119], v[116:117], v[118:119]
	v_mul_f32_e32 v136, v135, v135
	v_mul_f32_e32 v100, v88, v88
	v_mul_f32_e32 v114, v89, v89
	v_mul_f32_e32 v138, v116, v116
	v_mov_b32_e32 v139, v119
	v_pk_add_f32 v[118:119], v[138:139], v[136:137]
	v_pk_add_f32 v[100:101], v[100:101], v[114:115]
	v_lshlrev_b32_e32 v115, 16, v91
	v_lshlrev_b32_e32 v114, 16, v90
	v_and_b32_e32 v91, 0xffff0000, v91
	v_and_b32_e32 v90, 0xffff0000, v90
	v_pk_add_f32 v[100:101], v[118:119], v[100:101]
	v_pk_mul_f32 v[118:119], v[90:91], v[90:91]
	v_lshlrev_b32_e32 v136, 16, v84
	v_and_b32_e32 v137, 0xffff0000, v84
	v_lshlrev_b32_e32 v138, 16, v86
	v_lshlrev_b32_e32 v142, 16, v85
	v_pk_fma_f32 v[118:119], v[114:115], v[114:115], v[118:119]
	v_and_b32_e32 v146, 0xffff0000, v86
	v_lshlrev_b32_e32 v140, 16, v87
	v_and_b32_e32 v141, 0xffff0000, v87
	v_mul_f32_e32 v139, v136, v136
	v_mul_f32_e32 v87, v137, v137
	v_and_b32_e32 v143, 0xffff0000, v85
	v_mul_f32_e32 v84, v142, v142
	v_mov_b32_e32 v86, v138
	v_pk_add_f32 v[100:101], v[100:101], v[100:101] op_sel_hi:[0,1]
	v_pk_add_f32 v[118:119], v[118:119], v[118:119] op_sel_hi:[0,1]
	v_pk_fma_f32 v[84:85], v[142:143], v[142:143], v[84:85] op_sel_hi:[1,1,0]
	v_pk_add_f32 v[86:87], v[138:139], v[86:87]
	v_mul_f32_e32 v84, v146, v146
	v_mul_f32_e32 v118, v140, v140
	v_mul_f32_e32 v100, v141, v141
	v_mul_f32_e32 v144, v138, v138
	v_mov_b32_e32 v145, v87
	v_pk_add_f32 v[84:85], v[144:145], v[84:85]
	v_pk_add_f32 v[86:87], v[118:119], v[100:101]
	v_lshl_add_u64 v[118:119], s[50:51], 0, v[2:3]
	v_pk_add_f32 v[84:85], v[84:85], v[86:87]
	v_mov_b32_e32 v117, v135
	v_add_f32_e32 v84, v84, v85
	v_mov_b32_e32 v139, v146
	s_nop 1
	v_add_f32_dpp v84, v84, v84 quad_perm:[1,0,3,2] row_mask:0xf bank_mask:0xf
	s_nop 1
	v_add_f32_dpp v84, v84, v84 quad_perm:[2,3,0,1] row_mask:0xf bank_mask:0xf
	s_nop 1
	v_add_f32_dpp v84, v84, v84 row_half_mirror row_mask:0xf bank_mask:0xf
	s_nop 1
	v_add_f32_dpp v84, v84, v84 row_mirror row_mask:0xf bank_mask:0xf
	ds_bpermute_b32 v85, v131, v84
	s_waitcnt lgkmcnt(0)
	v_add_f32_e32 v84, v84, v85
	ds_bpermute_b32 v85, v134, v84
	s_waitcnt lgkmcnt(0)
	v_add_f32_e32 v84, v84, v85
	v_fmamk_f32 v84, v84, 0x3a000000, v234
	v_mul_f32_e32 v85, 0x4f800000, v84
	v_cmp_gt_f32_e32 vcc, s3, v84
	s_nop 1
	v_cndmask_b32_e32 v84, v84, v85, vcc
	v_sqrt_f32_e32 v85, v84
	s_nop 0
	v_add_u32_e32 v86, -1, v85
	v_fma_f32 v87, -v86, v85, v84
	v_cmp_ge_f32_e64 s[48:49], 0, v87
	v_add_u32_e32 v87, 1, v85
	s_nop 0
	v_cndmask_b32_e64 v86, v85, v86, s[48:49]
	v_fma_f32 v85, -v87, v85, v84
	v_cmp_lt_f32_e64 s[48:49], 0, v85
	s_nop 1
	v_cndmask_b32_e64 v85, v86, v87, s[48:49]
	v_mul_f32_e32 v86, 0x37800000, v85
	v_cndmask_b32_e32 v85, v85, v86, vcc
	v_cmp_class_f32_e32 vcc, v84, v235
	s_nop 1
	v_cndmask_b32_e32 v84, v85, v84, vcc
	v_div_scale_f32 v85, s[12:13], v84, v84, 1.0
	v_rcp_f32_e32 v86, v85
	s_nop 0
	v_fma_f32 v87, -v85, v86, 1.0
	v_fmac_f32_e32 v86, v87, v86
	v_div_scale_f32 v87, vcc, 1.0, v84, 1.0
	v_mul_f32_e32 v100, v87, v86
	v_fma_f32 v101, -v85, v100, v87
	v_fmac_f32_e32 v100, v101, v86
	v_fma_f32 v85, -v85, v100, v87
	v_div_fmas_f32 v85, v85, v86, v100
	v_div_fixup_f32 v100, v85, v84, 1.0
	v_mov_b32_e32 v84, v104
	v_mov_b32_e32 v85, v106
	v_mov_b32_e32 v86, v108
	v_mov_b32_e32 v87, v102
	v_mov_b32_e32 v102, v109
	v_pk_mul_f32 v[84:85], v[100:101], v[84:85] op_sel_hi:[0,1]
	v_pk_mul_f32 v[86:87], v[100:101], v[86:87] op_sel_hi:[0,1]
	v_mov_b32_e32 v106, v105
	v_pk_mul_f32 v[102:103], v[100:101], v[102:103] op_sel_hi:[0,1]
	v_pk_fma_f32 v[86:87], v[46:47], v[86:87], v[30:31]
	v_pk_fma_f32 v[84:85], v[44:45], v[84:85], v[28:29]
	v_pk_mul_f32 v[104:105], v[100:101], v[106:107] op_sel_hi:[0,1]
	v_pk_fma_f32 v[102:103], v[54:55], v[102:103], v[26:27]
	v_pk_fma_f32 v[104:105], v[52:53], v[104:105], v[24:25]
	v_cvt_pk_bf16_f32 v84, v84, v85
	v_cvt_pk_bf16_f32 v85, v86, v87
	v_cvt_pk_bf16_f32 v87, v102, v103
	v_add_co_u32_e32 v102, vcc, s24, v118
	v_cvt_pk_bf16_f32 v86, v104, v105
	s_nop 0
	v_addc_co_u32_e32 v103, vcc, 0, v119, vcc
	global_store_dwordx4 v[102:103], v[84:87], off
	v_pk_mul_f32 v[98:99], v[100:101], v[98:99] op_sel_hi:[0,1]
	v_pk_fma_f32 v[98:99], v[62:63], v[98:99], v[34:35]
	v_mov_b32_e32 v84, v112
	v_mov_b32_e32 v85, v96
	v_mov_b32_e32 v96, v113
	v_pk_mul_f32 v[84:85], v[100:101], v[84:85] op_sel_hi:[0,1]
	v_pk_mul_f32 v[86:87], v[100:101], v[96:97] op_sel_hi:[0,1]
	v_pk_mul_f32 v[96:97], v[100:101], v[110:111] op_sel_hi:[0,1]
	v_pk_fma_f32 v[86:87], v[58:59], v[86:87], v[38:39]
	v_pk_fma_f32 v[84:85], v[56:57], v[84:85], v[36:37]
	v_pk_fma_f32 v[96:97], v[60:61], v[96:97], v[32:33]
	v_cvt_pk_bf16_f32 v84, v84, v85
	v_cvt_pk_bf16_f32 v85, v86, v87
	v_cvt_pk_bf16_f32 v86, v96, v97
	v_cvt_pk_bf16_f32 v87, v98, v99
	global_store_dwordx4 v[102:103], v[84:87], off offset:1024
	s_nop 1
	v_pk_mul_f32 v[86:87], v[100:101], v[88:89] op_sel_hi:[0,1]
	v_mov_b32_e32 v88, v114
	v_mov_b32_e32 v89, v90
	v_mov_b32_e32 v90, v115
	v_pk_mul_f32 v[84:85], v[100:101], v[116:117] op_sel_hi:[0,1]
	v_pk_mul_f32 v[88:89], v[100:101], v[88:89] op_sel_hi:[0,1]
	v_pk_mul_f32 v[90:91], v[100:101], v[90:91] op_sel_hi:[0,1]
	v_pk_fma_f32 v[86:87], v[66:67], v[86:87], v[50:51]
	v_pk_fma_f32 v[84:85], v[64:65], v[84:85], v[48:49]
	v_pk_fma_f32 v[90:91], v[70:71], v[90:91], v[42:43]
	v_pk_fma_f32 v[88:89], v[68:69], v[88:89], v[40:41]
	v_cvt_pk_bf16_f32 v84, v84, v85
	v_cvt_pk_bf16_f32 v85, v86, v87
	v_cvt_pk_bf16_f32 v86, v88, v89
	v_cvt_pk_bf16_f32 v87, v90, v91
	global_store_dwordx4 v[102:103], v[84:87], off offset:2048
	v_pk_mul_f32 v[88:89], v[100:101], v[138:139] op_sel_hi:[0,1]
	v_pk_mul_f32 v[90:91], v[100:101], v[140:141] op_sel_hi:[0,1]
	v_pk_mul_f32 v[84:85], v[100:101], v[136:137] op_sel_hi:[0,1]
	v_pk_mul_f32 v[86:87], v[100:101], v[142:143] op_sel_hi:[0,1]
	s_waitcnt vmcnt(3)
	v_pk_fma_f32 v[86:87], v[82:83], v[86:87], v[78:79]
	v_pk_fma_f32 v[84:85], v[80:81], v[84:85], v[76:77]
	v_pk_fma_f32 v[90:91], v[94:95], v[90:91], v[74:75]
	v_pk_fma_f32 v[88:89], v[92:93], v[88:89], v[72:73]
	v_cvt_pk_bf16_f32 v84, v84, v85
	v_cvt_pk_bf16_f32 v85, v86, v87
	v_cvt_pk_bf16_f32 v86, v88, v89
	v_cvt_pk_bf16_f32 v87, v90, v91
	global_store_dwordx4 v[102:103], v[84:87], off offset:3072

.LBB0_458:
	s_add_i32 s8, s19, s23
	s_cmpk_lt_i32 s8, 0x1000
	s_cselect_b64 s[16:17], -1, 0
	s_and_b32 s9, s8, 0x3ff
	s_and_b32 s21, s8, 0xff
	s_cmpk_gt_i32 s8, 0xfff
	s_cselect_b64 s[58:59], -1, 0
	s_and_b64 s[60:61], s[58:59], exec
	s_cselect_b32 s12, s9, s21
	s_ashr_i32 s9, s8, 31
	s_mul_i32 s10, s8, 0x1600
	s_mul_hi_i32 s11, s8, 0x1600
	s_add_u32 s10, s15, s10
	s_addc_u32 s11, s18, s11
	s_waitcnt lgkmcnt(0)
	global_load_dwordx2 v[20:21], v56, s[10:11]
	global_load_dwordx4 v[16:19], v[28:29], off
	s_and_b32 s13, s12, 63
	s_lshr_b32 s12, s12, 6
	v_mov_b32_e32 v2, s12
	v_mov_b32_e32 v5, s13
	v_cndmask_b32_e64 v2, v2, v5, s[50:51]
	v_lshlrev_b32_e32 v2, 6, v2
	v_lshl_add_u64 v[8:9], v[26:27], 0, v[2:3]
	global_load_dwordx4 v[12:15], v[8:9], off
	v_lshl_add_u64 v[8:9], v[24:25], 0, v[2:3]
	global_load_dwordx4 v[8:11], v[8:9], off
	s_lshl_b32 s20, s21, 8
	s_waitcnt vmcnt(0)
	v_lshlrev_b32_e32 v23, 16, v21
	v_lshlrev_b32_e32 v22, 16, v20
	v_and_b32_e32 v21, 0xffff0000, v21
	v_and_b32_e32 v20, 0xffff0000, v20
	v_pk_mul_f32 v[76:77], v[20:21], v[20:21]
	s_nop 0
	v_pk_fma_f32 v[76:77], v[22:23], v[22:23], v[76:77]
	s_nop 0
	v_add_f32_e32 v2, v76, v77
	v_mov_b32_e32 v77, v20
	v_mov_b32_e32 v76, v22
	s_nop 1
	v_add_f32_dpp v2, v2, v2 quad_perm:[1,0,3,2] row_mask:0xf bank_mask:0xf
	s_nop 1
	v_add_f32_dpp v2, v2, v2 quad_perm:[2,3,0,1] row_mask:0xf bank_mask:0xf
	s_nop 1
	v_add_f32_dpp v2, v2, v2 row_half_mirror row_mask:0xf bank_mask:0xf
	s_nop 1
	v_add_f32_dpp v2, v2, v2 row_mirror row_mask:0xf bank_mask:0xf
	v_fmamk_f32 v2, v2, 0x3c800000, v234
	v_mul_f32_e32 v5, 0x4f800000, v2
	v_cmp_gt_f32_e32 vcc, s3, v2
	s_nop 1
	v_cndmask_b32_e32 v2, v2, v5, vcc
	v_sqrt_f32_e32 v5, v2
	s_nop 0
	v_add_u32_e32 v20, -1, v5
	v_add_u32_e32 v22, 1, v5
	v_fma_f32 v57, -v20, v5, v2
	v_fma_f32 v59, -v22, v5, v2
	v_cmp_ge_f32_e64 s[62:63], 0, v57
	s_nop 1
	v_cndmask_b32_e64 v5, v5, v20, s[62:63]
	v_cmp_lt_f32_e64 s[62:63], 0, v59
	s_nop 1
	v_cndmask_b32_e64 v5, v5, v22, s[62:63]
	v_mul_f32_e32 v20, 0x37800000, v5
	v_cndmask_b32_e32 v5, v5, v20, vcc
	v_cmp_class_f32_e32 vcc, v2, v235
	v_mov_b32_e32 v20, v23
	s_nop 0
	v_cndmask_b32_e32 v2, v5, v2, vcc
	v_div_scale_f32 v5, s[12:13], v2, v2, 1.0
	v_rcp_f32_e32 v22, v5
	v_div_scale_f32 v23, vcc, 1.0, v2, 1.0
	s_lshl_b64 s[12:13], s[8:9], 11
	v_fma_f32 v57, -v5, v22, 1.0
	v_fmac_f32_e32 v22, v57, v22
	v_mul_f32_e32 v57, v23, v22
	v_fma_f32 v59, -v5, v57, v23
	v_fmac_f32_e32 v57, v59, v22
	v_fma_f32 v5, -v5, v57, v23
	v_div_fmas_f32 v5, v5, v22, v57
	v_div_fixup_f32 v2, v5, v2, 1.0
	v_pk_mul_f32 v[22:23], v[2:3], v[76:77] op_sel_hi:[0,1]
	v_pk_mul_f32 v[20:21], v[2:3], v[20:21] op_sel_hi:[0,1]
	v_pk_mul_f32 v[18:19], v[18:19], v[20:21]
	v_pk_mul_f32 v[20:21], v[16:17], v[22:23]
	ds_bpermute_b32 v22, v70, v20
	ds_bpermute_b32 v23, v70, v21
	ds_bpermute_b32 v76, v70, v18
	ds_bpermute_b32 v77, v70, v19
	v_lshl_add_u64 v[16:17], v[54:55], 0, s[12:13]
	s_waitcnt lgkmcnt(2)
	v_pk_mul_f32 v[22:23], v[12:13], v[22:23]
	s_nop 0
	v_xor_b32_e32 v57, 0x80000000, v22
	s_waitcnt lgkmcnt(0)
	v_pk_mul_f32 v[76:77], v[14:15], v[76:77]
	v_xor_b32_e32 v59, 0x80000000, v23
	v_xor_b32_e32 v2, 0x80000000, v76
	v_xor_b32_e32 v5, 0x80000000, v77
	v_cndmask_b32_e64 v23, v23, v59, s[52:53]
	v_cndmask_b32_e64 v22, v22, v57, s[52:53]
	v_cndmask_b32_e64 v77, v77, v5, s[52:53]
	v_cndmask_b32_e64 v76, v76, v2, s[52:53]
	v_pk_fma_f32 v[76:77], v[10:11], v[18:19], v[76:77]
	v_pk_fma_f32 v[22:23], v[8:9], v[20:21], v[22:23]
	v_cndmask_b32_e64 v19, v19, v77, s[58:59]
	v_cndmask_b32_e64 v21, v21, v23, s[58:59]
	v_cndmask_b32_e64 v20, v20, v22, s[58:59]
	v_cndmask_b32_e64 v18, v18, v76, s[58:59]
	v_pk_mul_f32 v[18:19], v[18:19], s[46:47] op_sel_hi:[1,0]
	v_pk_mul_f32 v[20:21], v[20:21], s[46:47] op_sel_hi:[1,0]
	s_nop 0
	v_cvt_pk_bf16_f32 v20, v20, v21
	v_cvt_pk_bf16_f32 v21, v18, v19
	global_store_dwordx2 v[16:17], v[20:21], off
	global_load_dwordx2 v[22:23], v74, s[10:11] offset:512
	s_nop 0
	global_load_dwordx4 v[18:21], v[28:29], off
	s_waitcnt vmcnt(1)
	v_lshlrev_b32_e32 v77, 16, v23
	v_lshlrev_b32_e32 v76, 16, v22
	v_and_b32_e32 v23, 0xffff0000, v23
	v_and_b32_e32 v22, 0xffff0000, v22
	v_pk_mul_f32 v[78:79], v[22:23], v[22:23]
	s_nop 0
	v_pk_fma_f32 v[78:79], v[76:77], v[76:77], v[78:79]
	s_nop 0
	v_add_f32_e32 v2, v78, v79
	v_mov_b32_e32 v79, v22
	v_mov_b32_e32 v78, v76
	s_nop 1
	v_add_f32_dpp v2, v2, v2 quad_perm:[1,0,3,2] row_mask:0xf bank_mask:0xf
	s_nop 1
	v_add_f32_dpp v2, v2, v2 quad_perm:[2,3,0,1] row_mask:0xf bank_mask:0xf
	s_nop 1
	v_add_f32_dpp v2, v2, v2 row_half_mirror row_mask:0xf bank_mask:0xf
	s_nop 1
	v_add_f32_dpp v2, v2, v2 row_mirror row_mask:0xf bank_mask:0xf
	v_fmamk_f32 v2, v2, 0x3c800000, v234
	v_mul_f32_e32 v5, 0x4f800000, v2
	v_cmp_gt_f32_e32 vcc, s3, v2
	s_nop 1
	v_cndmask_b32_e32 v2, v2, v5, vcc
	v_sqrt_f32_e32 v5, v2
	s_nop 0
	v_add_u32_e32 v22, -1, v5
	v_add_u32_e32 v57, 1, v5
	v_fma_f32 v59, -v22, v5, v2
	v_fma_f32 v75, -v57, v5, v2
	v_cmp_ge_f32_e64 s[62:63], 0, v59
	s_nop 1
	v_cndmask_b32_e64 v5, v5, v22, s[62:63]
	v_cmp_lt_f32_e64 s[62:63], 0, v75
	s_nop 1
	v_cndmask_b32_e64 v5, v5, v57, s[62:63]
	v_mul_f32_e32 v22, 0x37800000, v5
	v_cndmask_b32_e32 v5, v5, v22, vcc
	v_cmp_class_f32_e32 vcc, v2, v235
	v_mov_b32_e32 v22, v77
	s_nop 0
	v_cndmask_b32_e32 v2, v5, v2, vcc
	v_div_scale_f32 v5, s[12:13], v2, v2, 1.0
	v_rcp_f32_e32 v57, v5
	v_div_scale_f32 v59, vcc, 1.0, v2, 1.0
	v_fma_f32 v75, -v5, v57, 1.0
	v_fmac_f32_e32 v57, v75, v57
	v_mul_f32_e32 v75, v59, v57
	v_fma_f32 v76, -v5, v75, v59
	v_fmac_f32_e32 v75, v76, v57
	v_fma_f32 v5, -v5, v75, v59
	v_div_fmas_f32 v5, v5, v57, v75
	v_div_fixup_f32 v2, v5, v2, 1.0
	v_pk_mul_f32 v[76:77], v[2:3], v[78:79] op_sel_hi:[0,1]
	v_pk_mul_f32 v[22:23], v[2:3], v[22:23] op_sel_hi:[0,1]
	s_waitcnt vmcnt(0)
	v_pk_mul_f32 v[20:21], v[20:21], v[22:23]
	v_pk_mul_f32 v[18:19], v[18:19], v[76:77]
	ds_bpermute_b32 v22, v70, v18
	ds_bpermute_b32 v23, v70, v19
	ds_bpermute_b32 v76, v70, v20
	ds_bpermute_b32 v77, v70, v21
	s_waitcnt lgkmcnt(2)
	v_pk_mul_f32 v[22:23], v[12:13], v[22:23]
	s_nop 0
	v_xor_b32_e32 v57, 0x80000000, v22
	s_waitcnt lgkmcnt(0)
	v_pk_mul_f32 v[76:77], v[14:15], v[76:77]
	v_xor_b32_e32 v59, 0x80000000, v23
	v_xor_b32_e32 v2, 0x80000000, v76
	v_xor_b32_e32 v5, 0x80000000, v77
	v_cndmask_b32_e64 v23, v23, v59, s[52:53]
	v_cndmask_b32_e64 v22, v22, v57, s[52:53]
	v_cndmask_b32_e64 v77, v77, v5, s[52:53]
	v_cndmask_b32_e64 v76, v76, v2, s[52:53]
	v_pk_fma_f32 v[76:77], v[10:11], v[20:21], v[76:77]
	v_pk_fma_f32 v[22:23], v[8:9], v[18:19], v[22:23]
	v_cndmask_b32_e64 v21, v21, v77, s[58:59]
	v_cndmask_b32_e64 v19, v19, v23, s[58:59]
	v_cndmask_b32_e64 v18, v18, v22, s[58:59]
	v_cndmask_b32_e64 v20, v20, v76, s[58:59]
	v_pk_mul_f32 v[20:21], v[20:21], s[46:47] op_sel_hi:[1,0]
	v_pk_mul_f32 v[18:19], v[18:19], s[46:47] op_sel_hi:[1,0]
	s_nop 0
	v_cvt_pk_bf16_f32 v18, v18, v19
	v_cvt_pk_bf16_f32 v19, v20, v21
	global_store_dwordx2 v[16:17], v[18:19], off offset:512
	global_load_dwordx2 v[22:23], v74, s[10:11] offset:1024
	s_nop 0
	global_load_dwordx4 v[18:21], v[28:29], off
	s_waitcnt vmcnt(1)
	v_lshlrev_b32_e32 v77, 16, v23
	v_lshlrev_b32_e32 v76, 16, v22
	v_and_b32_e32 v23, 0xffff0000, v23
	v_and_b32_e32 v22, 0xffff0000, v22
	v_pk_mul_f32 v[78:79], v[22:23], v[22:23]
	s_nop 0
	v_pk_fma_f32 v[78:79], v[76:77], v[76:77], v[78:79]
	s_nop 0
	v_add_f32_e32 v2, v78, v79
	v_mov_b32_e32 v79, v22
	v_mov_b32_e32 v78, v76
	s_nop 1
	v_add_f32_dpp v2, v2, v2 quad_perm:[1,0,3,2] row_mask:0xf bank_mask:0xf
	s_nop 1
	v_add_f32_dpp v2, v2, v2 quad_perm:[2,3,0,1] row_mask:0xf bank_mask:0xf
	s_nop 1
	v_add_f32_dpp v2, v2, v2 row_half_mirror row_mask:0xf bank_mask:0xf
	s_nop 1
	v_add_f32_dpp v2, v2, v2 row_mirror row_mask:0xf bank_mask:0xf
	v_fmamk_f32 v2, v2, 0x3c800000, v234
	v_mul_f32_e32 v5, 0x4f800000, v2
	v_cmp_gt_f32_e32 vcc, s3, v2
	s_nop 1
	v_cndmask_b32_e32 v2, v2, v5, vcc
	v_sqrt_f32_e32 v5, v2
	s_nop 0
	v_add_u32_e32 v22, -1, v5
	v_add_u32_e32 v57, 1, v5
	v_fma_f32 v59, -v22, v5, v2
	v_fma_f32 v75, -v57, v5, v2
	v_cmp_ge_f32_e64 s[62:63], 0, v59
	s_nop 1
	v_cndmask_b32_e64 v5, v5, v22, s[62:63]
	v_cmp_lt_f32_e64 s[62:63], 0, v75
	s_nop 1
	v_cndmask_b32_e64 v5, v5, v57, s[62:63]
	v_mul_f32_e32 v22, 0x37800000, v5
	v_cndmask_b32_e32 v5, v5, v22, vcc
	v_cmp_class_f32_e32 vcc, v2, v235
	v_mov_b32_e32 v22, v77
	s_nop 0
	v_cndmask_b32_e32 v2, v5, v2, vcc
	v_div_scale_f32 v5, s[12:13], v2, v2, 1.0
	v_rcp_f32_e32 v57, v5
	v_div_scale_f32 v59, vcc, 1.0, v2, 1.0
	v_fma_f32 v75, -v5, v57, 1.0
	v_fmac_f32_e32 v57, v75, v57
	v_mul_f32_e32 v75, v59, v57
	v_fma_f32 v76, -v5, v75, v59
	v_fmac_f32_e32 v75, v76, v57
	v_fma_f32 v5, -v5, v75, v59
	v_div_fmas_f32 v5, v5, v57, v75
	v_div_fixup_f32 v2, v5, v2, 1.0
	v_pk_mul_f32 v[76:77], v[2:3], v[78:79] op_sel_hi:[0,1]
	v_pk_mul_f32 v[22:23], v[2:3], v[22:23] op_sel_hi:[0,1]
	s_waitcnt vmcnt(0)
	v_pk_mul_f32 v[20:21], v[20:21], v[22:23]
	v_pk_mul_f32 v[18:19], v[18:19], v[76:77]
	ds_bpermute_b32 v22, v70, v18
	ds_bpermute_b32 v23, v70, v19
	ds_bpermute_b32 v76, v70, v20
	ds_bpermute_b32 v77, v70, v21
	s_waitcnt lgkmcnt(2)
	v_pk_mul_f32 v[22:23], v[12:13], v[22:23]
	s_nop 0
	v_xor_b32_e32 v57, 0x80000000, v22
	s_waitcnt lgkmcnt(0)
	v_pk_mul_f32 v[76:77], v[14:15], v[76:77]
	v_xor_b32_e32 v59, 0x80000000, v23
	v_xor_b32_e32 v2, 0x80000000, v76
	v_xor_b32_e32 v5, 0x80000000, v77
	v_cndmask_b32_e64 v23, v23, v59, s[52:53]
	v_cndmask_b32_e64 v22, v22, v57, s[52:53]
	v_cndmask_b32_e64 v77, v77, v5, s[52:53]
	v_cndmask_b32_e64 v76, v76, v2, s[52:53]
	v_pk_fma_f32 v[76:77], v[10:11], v[20:21], v[76:77]
	v_pk_fma_f32 v[22:23], v[8:9], v[18:19], v[22:23]
	v_cndmask_b32_e64 v21, v21, v77, s[58:59]
	v_cndmask_b32_e64 v19, v19, v23, s[58:59]
	v_cndmask_b32_e64 v18, v18, v22, s[58:59]
	v_cndmask_b32_e64 v20, v20, v76, s[58:59]
	v_pk_mul_f32 v[20:21], v[20:21], s[46:47] op_sel_hi:[1,0]
	v_pk_mul_f32 v[18:19], v[18:19], s[46:47] op_sel_hi:[1,0]
	s_nop 0
	v_cvt_pk_bf16_f32 v18, v18, v19
	v_cvt_pk_bf16_f32 v19, v20, v21
	global_store_dwordx2 v[16:17], v[18:19], off offset:1024
	global_load_dwordx2 v[22:23], v74, s[10:11] offset:1536
	s_nop 0
	global_load_dwordx4 v[18:21], v[28:29], off
	s_waitcnt vmcnt(1)
	v_lshlrev_b32_e32 v77, 16, v23
	v_lshlrev_b32_e32 v76, 16, v22
	v_and_b32_e32 v23, 0xffff0000, v23
	v_and_b32_e32 v22, 0xffff0000, v22
	v_pk_mul_f32 v[78:79], v[22:23], v[22:23]
	s_nop 0
	v_pk_fma_f32 v[78:79], v[76:77], v[76:77], v[78:79]
	s_nop 0
	v_add_f32_e32 v2, v78, v79
	v_mov_b32_e32 v79, v22
	v_mov_b32_e32 v78, v76
	s_nop 1
	v_add_f32_dpp v2, v2, v2 quad_perm:[1,0,3,2] row_mask:0xf bank_mask:0xf
	s_nop 1
	v_add_f32_dpp v2, v2, v2 quad_perm:[2,3,0,1] row_mask:0xf bank_mask:0xf
	s_nop 1
	v_add_f32_dpp v2, v2, v2 row_half_mirror row_mask:0xf bank_mask:0xf
	s_nop 1
	v_add_f32_dpp v2, v2, v2 row_mirror row_mask:0xf bank_mask:0xf
	v_fmamk_f32 v2, v2, 0x3c800000, v234
	v_mul_f32_e32 v5, 0x4f800000, v2
	v_cmp_gt_f32_e32 vcc, s3, v2
	s_nop 1
	v_cndmask_b32_e32 v2, v2, v5, vcc
	v_sqrt_f32_e32 v5, v2
	s_nop 0
	v_add_u32_e32 v22, -1, v5
	v_add_u32_e32 v57, 1, v5
	v_fma_f32 v59, -v22, v5, v2
	v_fma_f32 v75, -v57, v5, v2
	v_cmp_ge_f32_e64 s[62:63], 0, v59
	s_nop 1
	v_cndmask_b32_e64 v5, v5, v22, s[62:63]
	v_cmp_lt_f32_e64 s[62:63], 0, v75
	s_nop 1
	v_cndmask_b32_e64 v5, v5, v57, s[62:63]
	v_mul_f32_e32 v22, 0x37800000, v5
	v_cndmask_b32_e32 v5, v5, v22, vcc
	v_cmp_class_f32_e32 vcc, v2, v235
	v_mov_b32_e32 v22, v77
	s_nop 0
	v_cndmask_b32_e32 v2, v5, v2, vcc
	v_div_scale_f32 v5, s[12:13], v2, v2, 1.0
	v_rcp_f32_e32 v57, v5
	v_div_scale_f32 v59, vcc, 1.0, v2, 1.0
	v_fma_f32 v75, -v5, v57, 1.0
	v_fmac_f32_e32 v57, v75, v57
	v_mul_f32_e32 v75, v59, v57
	v_fma_f32 v76, -v5, v75, v59
	v_fmac_f32_e32 v75, v76, v57
	v_fma_f32 v5, -v5, v75, v59
	v_div_fmas_f32 v5, v5, v57, v75
	v_div_fixup_f32 v2, v5, v2, 1.0
	v_pk_mul_f32 v[76:77], v[2:3], v[78:79] op_sel_hi:[0,1]
	v_pk_mul_f32 v[22:23], v[2:3], v[22:23] op_sel_hi:[0,1]
	s_waitcnt vmcnt(0)
	v_pk_mul_f32 v[20:21], v[20:21], v[22:23]
	v_pk_mul_f32 v[18:19], v[18:19], v[76:77]
	ds_bpermute_b32 v22, v70, v18
	ds_bpermute_b32 v23, v70, v19
	ds_bpermute_b32 v76, v70, v20
	ds_bpermute_b32 v77, v70, v21
	s_waitcnt lgkmcnt(2)
	v_pk_mul_f32 v[22:23], v[12:13], v[22:23]
	s_nop 0
	v_xor_b32_e32 v57, 0x80000000, v22
	s_waitcnt lgkmcnt(0)
	v_pk_mul_f32 v[76:77], v[14:15], v[76:77]
	v_xor_b32_e32 v59, 0x80000000, v23
	v_xor_b32_e32 v2, 0x80000000, v76
	v_xor_b32_e32 v5, 0x80000000, v77
	v_cndmask_b32_e64 v23, v23, v59, s[52:53]
	v_cndmask_b32_e64 v22, v22, v57, s[52:53]
	v_cndmask_b32_e64 v77, v77, v5, s[52:53]
	v_cndmask_b32_e64 v76, v76, v2, s[52:53]
	v_pk_fma_f32 v[76:77], v[10:11], v[20:21], v[76:77]
	v_pk_fma_f32 v[22:23], v[8:9], v[18:19], v[22:23]
	v_cndmask_b32_e64 v21, v21, v77, s[58:59]
	v_cndmask_b32_e64 v19, v19, v23, s[58:59]
	v_cndmask_b32_e64 v18, v18, v22, s[58:59]
	v_cndmask_b32_e64 v20, v20, v76, s[58:59]
	v_pk_mul_f32 v[20:21], v[20:21], s[46:47] op_sel_hi:[1,0]
	v_pk_mul_f32 v[18:19], v[18:19], s[46:47] op_sel_hi:[1,0]
	s_nop 0
	v_cvt_pk_bf16_f32 v18, v18, v19
	v_cvt_pk_bf16_f32 v19, v20, v21
	global_store_dwordx2 v[16:17], v[18:19], off offset:1536
	global_load_dwordx2 v[20:21], v56, s[10:11] offset:2048
	s_nop 0
	global_load_dwordx4 v[16:19], v[30:31], off
	s_waitcnt vmcnt(1)
	v_lshlrev_b32_e32 v23, 16, v21
	v_lshlrev_b32_e32 v22, 16, v20
	v_and_b32_e32 v21, 0xffff0000, v21
	v_and_b32_e32 v20, 0xffff0000, v20
	v_pk_mul_f32 v[76:77], v[20:21], v[20:21]
	s_nop 0
	v_pk_fma_f32 v[76:77], v[22:23], v[22:23], v[76:77]
	s_nop 0
	v_add_f32_e32 v2, v76, v77
	v_mov_b32_e32 v77, v20
	v_mov_b32_e32 v76, v22
	s_nop 1
	v_add_f32_dpp v2, v2, v2 quad_perm:[1,0,3,2] row_mask:0xf bank_mask:0xf
	s_nop 1
	v_add_f32_dpp v2, v2, v2 quad_perm:[2,3,0,1] row_mask:0xf bank_mask:0xf
	s_nop 1
	v_add_f32_dpp v2, v2, v2 row_half_mirror row_mask:0xf bank_mask:0xf
	s_nop 1
	v_add_f32_dpp v2, v2, v2 row_mirror row_mask:0xf bank_mask:0xf
	v_fmamk_f32 v2, v2, 0x3c800000, v234
	v_mul_f32_e32 v5, 0x4f800000, v2
	v_cmp_gt_f32_e32 vcc, s3, v2
	s_nop 1
	v_cndmask_b32_e32 v2, v2, v5, vcc
	v_sqrt_f32_e32 v5, v2
	s_nop 0
	v_add_u32_e32 v20, -1, v5
	v_add_u32_e32 v22, 1, v5
	v_fma_f32 v57, -v20, v5, v2
	v_fma_f32 v59, -v22, v5, v2
	v_cmp_ge_f32_e64 s[62:63], 0, v57
	s_nop 1
	v_cndmask_b32_e64 v5, v5, v20, s[62:63]
	v_cmp_lt_f32_e64 s[62:63], 0, v59
	s_nop 1
	v_cndmask_b32_e64 v5, v5, v22, s[62:63]
	v_mul_f32_e32 v20, 0x37800000, v5
	v_cndmask_b32_e32 v5, v5, v20, vcc
	v_cmp_class_f32_e32 vcc, v2, v235
	v_mov_b32_e32 v20, v23
	s_nop 0
	v_cndmask_b32_e32 v2, v5, v2, vcc
	v_div_scale_f32 v5, s[12:13], v2, v2, 1.0
	v_rcp_f32_e32 v22, v5
	v_div_scale_f32 v23, vcc, 1.0, v2, 1.0
	v_fma_f32 v57, -v5, v22, 1.0
	v_fmac_f32_e32 v22, v57, v22
	v_mul_f32_e32 v57, v23, v22
	v_fma_f32 v59, -v5, v57, v23
	v_fmac_f32_e32 v57, v59, v22
	v_fma_f32 v5, -v5, v57, v23
	v_div_fmas_f32 v5, v5, v22, v57
	v_div_fixup_f32 v2, v5, v2, 1.0
	v_pk_mul_f32 v[22:23], v[2:3], v[76:77] op_sel_hi:[0,1]
	v_pk_mul_f32 v[20:21], v[2:3], v[20:21] op_sel_hi:[0,1]
	s_waitcnt vmcnt(0)
	v_pk_mul_f32 v[18:19], v[18:19], v[20:21]
	v_pk_mul_f32 v[16:17], v[16:17], v[22:23]
	s_mov_b64 vcc, s[60:61]
	s_cbranch_vccnz .LBB0_460
	s_lshl_b32 s90, s20, 2
	v_lshl_add_u64 v[20:21], v[62:63], 0, s[90:91]
	global_store_dwordx4 v[20:21], v[16:19], off

.LBB0_462:
	s_lshl_b32 s90, s21, 1
	s_nop 0
	v_lshl_add_u64 v[18:19], v[60:61], 0, s[90:91]
	s_waitcnt vmcnt(0)
	global_store_short v[18:19], v16, off
	global_store_short_d16_hi v[18:19], v16, off offset:512
	global_store_short v[18:19], v17, off offset:1024
	global_store_short_d16_hi v[18:19], v17, off offset:1536
	global_load_dwordx4 v[16:19], v4, s[10:11] offset:3072
	s_nop 0
	global_load_dwordx4 v[20:23], v[36:37], off offset:16
	global_load_dwordx4 v[76:79], v[36:37], off
	s_lshl_b64 s[12:13], s[8:9], 10
	s_waitcnt vmcnt(2)
	v_lshlrev_b32_e32 v84, 16, v16
	v_and_b32_e32 v85, 0xffff0000, v16
	v_lshlrev_b32_e32 v80, 16, v19
	v_and_b32_e32 v81, 0xffff0000, v19
	v_lshlrev_b32_e32 v82, 16, v18
	v_and_b32_e32 v83, 0xffff0000, v18
	v_lshlrev_b32_e32 v18, 16, v17
	v_and_b32_e32 v19, 0xffff0000, v17
	v_pk_mul_f32 v[90:91], v[84:85], v[84:85]
	v_pk_mul_f32 v[88:89], v[18:19], v[18:19]
	v_add_f32_e32 v2, v90, v91
	v_add_f32_e32 v2, v88, v2
	v_pk_mul_f32 v[86:87], v[82:83], v[82:83]
	v_add_f32_e32 v2, v89, v2
	v_add_f32_e32 v2, v86, v2
	v_pk_mul_f32 v[16:17], v[80:81], v[80:81]
	v_add_f32_e32 v2, v87, v2
	v_add_f32_e32 v2, v16, v2
	v_add_f32_e32 v2, v17, v2
	v_lshl_add_u64 v[86:87], v[38:39], 0, s[12:13]
	s_nop 1
	v_add_f32_dpp v2, v2, v2 quad_perm:[1,0,3,2] row_mask:0xf bank_mask:0xf
	s_nop 1
	v_add_f32_dpp v2, v2, v2 quad_perm:[2,3,0,1] row_mask:0xf bank_mask:0xf
	s_nop 1
	v_add_f32_dpp v2, v2, v2 row_half_mirror row_mask:0xf bank_mask:0xf
	s_nop 1
	v_add_f32_dpp v2, v2, v2 row_mirror row_mask:0xf bank_mask:0xf
	ds_bpermute_b32 v5, v72, v2
	s_waitcnt lgkmcnt(0)
	v_add_f32_e32 v2, v2, v5
	ds_bpermute_b32 v16, v73, v2
	v_mov_b32_e32 v5, v3
	s_waitcnt lgkmcnt(0)
	v_add_f32_e32 v2, v2, v16
	v_fmamk_f32 v2, v2, 0x3b000000, v234
	v_mul_f32_e32 v16, 0x4f800000, v2
	v_cmp_gt_f32_e32 vcc, s3, v2
	s_nop 1
	v_cndmask_b32_e32 v2, v2, v16, vcc
	v_sqrt_f32_e32 v57, v2
	v_lshl_add_u64 v[16:17], s[10:11], 0, v[4:5]
	v_add_u32_e32 v5, -1, v57
	v_add_u32_e32 v59, 1, v57
	v_fma_f32 v75, -v5, v57, v2
	v_fma_f32 v88, -v59, v57, v2
	v_cmp_ge_f32_e64 s[62:63], 0, v75
	s_nop 1
	v_cndmask_b32_e64 v5, v57, v5, s[62:63]
	v_cmp_lt_f32_e64 s[62:63], 0, v88
	s_nop 1
	v_cndmask_b32_e64 v5, v5, v59, s[62:63]
	v_mul_f32_e32 v57, 0x37800000, v5
	v_cndmask_b32_e32 v5, v5, v57, vcc
	v_cmp_class_f32_e32 vcc, v2, v235
	s_nop 1
	v_cndmask_b32_e32 v2, v5, v2, vcc
	v_div_scale_f32 v5, s[16:17], v2, v2, 1.0
	v_rcp_f32_e32 v57, v5
	v_add_co_u32_e32 v88, vcc, s28, v16
	s_nop 1
	v_addc_co_u32_e32 v89, vcc, 0, v17, vcc
	v_fma_f32 v17, -v5, v57, 1.0
	v_div_scale_f32 v16, vcc, 1.0, v2, 1.0
	v_fmac_f32_e32 v57, v17, v57
	v_mul_f32_e32 v17, v16, v57
	v_fma_f32 v59, -v5, v17, v16
	v_fmac_f32_e32 v17, v59, v57
	v_fma_f32 v5, -v5, v17, v16
	v_div_fmas_f32 v5, v5, v57, v17
	v_div_fixup_f32 v2, v5, v2, 1.0
	s_waitcnt vmcnt(0)
	v_pk_mul_f32 v[16:17], v[76:77], v[2:3] op_sel_hi:[1,0]
	v_pk_mul_f32 v[76:77], v[78:79], v[2:3] op_sel_hi:[1,0]
	v_pk_mul_f32 v[20:21], v[20:21], v[2:3] op_sel_hi:[1,0]
	v_pk_mul_f32 v[22:23], v[22:23], v[2:3] op_sel_hi:[1,0]
	v_pk_mul_f32 v[16:17], v[16:17], v[84:85]
	v_pk_mul_f32 v[18:19], v[76:77], v[18:19]
	v_pk_mul_f32 v[20:21], v[20:21], v[82:83]
	v_pk_mul_f32 v[22:23], v[22:23], v[80:81]
	v_cvt_pk_bf16_f32 v16, v16, v17
	v_cvt_pk_bf16_f32 v17, v18, v19
	v_cvt_pk_bf16_f32 v18, v20, v21
	v_cvt_pk_bf16_f32 v19, v22, v23
	global_store_dwordx4 v[86:87], v[16:19], off
	global_load_dwordx4 v[16:19], v[88:89], off
	s_nop 0
	global_load_dwordx4 v[20:23], v[40:41], off offset:16
	global_load_dwordx4 v[76:79], v[40:41], off
	s_waitcnt vmcnt(2)
	v_lshlrev_b32_e32 v80, 16, v16
	v_and_b32_e32 v81, 0xffff0000, v16
	v_lshlrev_b32_e32 v16, 16, v17
	v_and_b32_e32 v17, 0xffff0000, v17
	v_pk_mul_f32 v[84:85], v[80:81], v[80:81]
	v_pk_mul_f32 v[86:87], v[16:17], v[16:17]
	v_add_f32_e32 v2, v84, v85
	v_lshlrev_b32_e32 v82, 16, v18
	v_and_b32_e32 v83, 0xffff0000, v18
	v_add_f32_e32 v2, v86, v2
	v_pk_mul_f32 v[88:89], v[82:83], v[82:83]
	v_add_f32_e32 v2, v87, v2
	v_lshlrev_b32_e32 v18, 16, v19
	v_and_b32_e32 v19, 0xffff0000, v19
	v_add_f32_e32 v2, v88, v2
	v_pk_mul_f32 v[90:91], v[18:19], v[18:19]
	v_add_f32_e32 v2, v89, v2
	v_add_f32_e32 v2, v90, v2
	v_add_f32_e32 v2, v91, v2
	s_nop 1
	v_add_f32_dpp v2, v2, v2 quad_perm:[1,0,3,2] row_mask:0xf bank_mask:0xf
	s_nop 1
	v_add_f32_dpp v2, v2, v2 quad_perm:[2,3,0,1] row_mask:0xf bank_mask:0xf
	s_nop 1
	v_add_f32_dpp v2, v2, v2 row_half_mirror row_mask:0xf bank_mask:0xf
	s_nop 1
	v_add_f32_dpp v2, v2, v2 row_mirror row_mask:0xf bank_mask:0xf
	ds_bpermute_b32 v5, v72, v2
	s_waitcnt lgkmcnt(0)
	v_add_f32_e32 v2, v2, v5
	ds_bpermute_b32 v5, v73, v2
	s_waitcnt lgkmcnt(0)
	v_add_f32_e32 v2, v2, v5
	v_fmamk_f32 v2, v2, 0x3b000000, v234
	v_mul_f32_e32 v5, 0x4f800000, v2
	v_cmp_gt_f32_e32 vcc, s3, v2
	s_nop 1
	v_cndmask_b32_e32 v2, v2, v5, vcc
	v_sqrt_f32_e32 v5, v2
	s_nop 0
	v_add_u32_e32 v57, -1, v5
	v_add_u32_e32 v59, 1, v5
	v_fma_f32 v75, -v57, v5, v2
	v_fma_f32 v84, -v59, v5, v2
	v_cmp_ge_f32_e64 s[62:63], 0, v75
	s_nop 1
	v_cndmask_b32_e64 v5, v5, v57, s[62:63]
	v_cmp_lt_f32_e64 s[62:63], 0, v84
	v_lshl_add_u64 v[84:85], v[42:43], 0, s[12:13]
	s_nop 0
	v_cndmask_b32_e64 v5, v5, v59, s[62:63]
	v_mul_f32_e32 v57, 0x37800000, v5
	v_cndmask_b32_e32 v5, v5, v57, vcc
	v_cmp_class_f32_e32 vcc, v2, v235
	s_nop 1
	v_cndmask_b32_e32 v2, v5, v2, vcc
	v_div_scale_f32 v5, s[16:17], v2, v2, 1.0
	v_rcp_f32_e32 v57, v5
	v_div_scale_f32 v59, vcc, 1.0, v2, 1.0
	v_fma_f32 v75, -v5, v57, 1.0
	v_fmac_f32_e32 v57, v75, v57
	v_mul_f32_e32 v75, v59, v57
	v_fma_f32 v86, -v5, v75, v59
	v_fmac_f32_e32 v75, v86, v57
	v_fma_f32 v5, -v5, v75, v59
	v_div_fmas_f32 v5, v5, v57, v75
	v_div_fixup_f32 v2, v5, v2, 1.0
	s_waitcnt vmcnt(0)
	v_pk_mul_f32 v[76:77], v[76:77], v[2:3] op_sel_hi:[1,0]
	v_pk_mul_f32 v[78:79], v[78:79], v[2:3] op_sel_hi:[1,0]
	v_pk_mul_f32 v[86:87], v[20:21], v[2:3] op_sel_hi:[1,0]
	v_pk_mul_f32 v[88:89], v[22:23], v[2:3] op_sel_hi:[1,0]
	v_pk_mul_f32 v[20:21], v[76:77], v[80:81]
	v_pk_mul_f32 v[22:23], v[78:79], v[16:17]
	v_pk_mul_f32 v[16:17], v[86:87], v[82:83]
	v_pk_mul_f32 v[18:19], v[88:89], v[18:19]
	v_cvt_pk_bf16_f32 v76, v20, v21
	v_cvt_pk_bf16_f32 v77, v22, v23
	v_cvt_pk_bf16_f32 v78, v16, v17
	v_cvt_pk_bf16_f32 v79, v18, v19
	s_and_b64 vcc, exec, s[60:61]
	global_store_dwordx4 v[84:85], v[76:79], off
	s_cbranch_vccnz .LBB0_464
	s_lshl_b32 s90, s21, 11
	v_lshl_add_u64 v[76:77], v[66:67], 0, s[90:91]
	global_store_dwordx4 v[76:77], v[20:23], off
	global_store_dwordx4 v[76:77], v[16:19], off offset:16

.LBB0_1544:
	global_load_dwordx4 v[44:47], v[48:49], off
	global_load_dwordx4 v[40:43], v[48:49], off offset:1024
	global_load_dwordx4 v[36:39], v[48:49], off offset:2048
	global_load_dwordx4 v[32:35], v[48:49], off offset:3072
	s_add_i32 s2, s2, s94
	v_lshl_add_u64 v[48:49], v[48:49], 0, s[4:5]
	s_cmpk_lt_i32 s2, 0x3000
	s_waitcnt vmcnt(0)
	v_lshlrev_b32_e32 v61, 16, v46
	v_and_b32_e32 v63, 0xffff0000, v46
	v_and_b32_e32 v62, 0xffff0000, v44
	v_lshlrev_b32_e32 v65, 16, v47
	v_and_b32_e32 v47, 0xffff0000, v47
	v_and_b32_e32 v46, 0xffff0000, v45
	v_lshlrev_b32_e32 v60, 16, v44
	v_lshlrev_b32_e32 v64, 16, v45
	v_lshlrev_b32_e32 v67, 16, v41
	v_lshlrev_b32_e32 v66, 16, v40
	v_and_b32_e32 v41, 0xffff0000, v41
	v_and_b32_e32 v40, 0xffff0000, v40
	v_pk_mul_f32 v[76:77], v[62:63], v[62:63]
	v_pk_mul_f32 v[78:79], v[46:47], v[46:47]
	v_lshlrev_b32_e32 v44, 16, v42
	v_and_b32_e32 v45, 0xffff0000, v42
	v_lshlrev_b32_e32 v42, 16, v43
	v_lshlrev_b32_e32 v68, 16, v36
	v_pk_mul_f32 v[80:81], v[40:41], v[40:41]
	v_mov_b32_e32 v96, v60
	v_mov_b32_e32 v97, v62
	v_mov_b32_e32 v98, v64
	v_mov_b32_e32 v99, v46
	v_mov_b32_e32 v62, v61
	v_mov_b32_e32 v46, v65
	v_pk_fma_f32 v[60:61], v[60:61], v[60:61], v[76:77]
	v_pk_fma_f32 v[64:65], v[64:65], v[64:65], v[78:79]
	v_and_b32_e32 v43, 0xffff0000, v43
	v_and_b32_e32 v85, 0xffff0000, v36
	v_lshlrev_b32_e32 v71, 16, v39
	v_lshlrev_b32_e32 v70, 16, v38
	v_and_b32_e32 v39, 0xffff0000, v39
	v_and_b32_e32 v38, 0xffff0000, v38
	v_mul_f32_e32 v69, v44, v44
	v_mul_f32_e32 v83, v45, v45
	v_mul_f32_e32 v84, v42, v42
	v_mov_b32_e32 v82, v68
	v_mov_b32_e32 v100, v66
	v_mov_b32_e32 v101, v40
	v_mov_b32_e32 v40, v67
	v_pk_fma_f32 v[66:67], v[66:67], v[66:67], v[80:81]
	v_pk_add_f32 v[60:61], v[60:61], v[64:65]
	v_lshlrev_b32_e32 v36, 16, v37
	v_and_b32_e32 v37, 0xffff0000, v37
	v_pk_mul_f32 v[88:89], v[38:39], v[38:39]
	v_pk_fma_f32 v[76:77], v[42:43], v[42:43], v[84:85] op_sel_hi:[1,1,0]
	v_pk_add_f32 v[78:79], v[68:69], v[82:83]
	v_pk_add_f32 v[64:65], v[66:67], v[66:67] op_sel_hi:[0,1]
	v_pk_add_f32 v[60:61], v[60:61], v[60:61] op_sel_hi:[0,1]
	v_mul_f32_e32 v86, v68, v68
	v_mov_b32_e32 v102, v70
	v_mov_b32_e32 v103, v38
	v_mov_b32_e32 v38, v71
	v_pk_fma_f32 v[70:71], v[70:71], v[70:71], v[88:89]
	v_mul_f32_e32 v76, v85, v85
	v_mov_b32_e32 v87, v79
	v_mul_f32_e32 v64, v37, v37
	v_mul_f32_e32 v60, v36, v36
	v_lshlrev_b32_e32 v72, 16, v32
	v_and_b32_e32 v73, 0xffff0000, v32
	v_lshlrev_b32_e32 v32, 16, v34
	v_lshlrev_b32_e32 v74, 16, v33
	v_pk_add_f32 v[66:67], v[70:71], v[70:71] op_sel_hi:[0,1]
	v_pk_add_f32 v[70:71], v[86:87], v[76:77]
	v_pk_add_f32 v[60:61], v[60:61], v[64:65]
	v_and_b32_e32 v93, 0xffff0000, v34
	v_and_b32_e32 v75, 0xffff0000, v33
	v_mul_f32_e32 v33, v72, v72
	v_mul_f32_e32 v91, v73, v73
	v_mul_f32_e32 v92, v74, v74
	v_mov_b32_e32 v90, v32
	v_pk_add_f32 v[60:61], v[70:71], v[60:61]
	v_lshlrev_b32_e32 v34, 16, v35
	v_and_b32_e32 v35, 0xffff0000, v35
	v_pk_fma_f32 v[80:81], v[74:75], v[74:75], v[92:93] op_sel_hi:[1,1,0]
	v_pk_add_f32 v[82:83], v[32:33], v[90:91]
	v_pk_add_f32 v[60:61], v[60:61], v[60:61] op_sel_hi:[0,1]
	v_mul_f32_e32 v94, v32, v32
	v_mul_f32_e32 v80, v93, v93
	v_mov_b32_e32 v95, v83
	v_mul_f32_e32 v66, v34, v34
	v_mul_f32_e32 v60, v35, v35
	v_pk_add_f32 v[76:77], v[94:95], v[80:81]
	v_pk_add_f32 v[60:61], v[66:67], v[60:61]
	v_mov_b32_e32 v69, v85
	v_pk_add_f32 v[60:61], v[76:77], v[60:61]
	v_mov_b32_e32 v33, v93
	v_add_f32_e32 v60, v60, v61
	s_nop 1
	v_add_f32_dpp v60, v60, v60 quad_perm:[1,0,3,2] row_mask:0xf bank_mask:0xf
	s_nop 1
	v_add_f32_dpp v60, v60, v60 quad_perm:[2,3,0,1] row_mask:0xf bank_mask:0xf
	s_nop 1
	v_add_f32_dpp v60, v60, v60 row_half_mirror row_mask:0xf bank_mask:0xf
	s_nop 1
	v_add_f32_dpp v60, v60, v60 row_mirror row_mask:0xf bank_mask:0xf
	ds_bpermute_b32 v61, v56, v60
	s_waitcnt lgkmcnt(0)
	v_add_f32_e32 v60, v60, v61
	ds_bpermute_b32 v61, v57, v60
	s_waitcnt lgkmcnt(0)
	v_add_f32_e32 v60, v60, v61
	v_fmamk_f32 v60, v60, 0x3a000000, v58
	v_mul_f32_e32 v61, 0x4f800000, v60
	v_cmp_gt_f32_e32 vcc, s3, v60
	s_nop 1
	v_cndmask_b32_e32 v60, v60, v61, vcc
	v_sqrt_f32_e32 v61, v60
	s_nop 0
	v_add_u32_e32 v64, -1, v61
	v_add_u32_e32 v65, 1, v61
	v_fma_f32 v66, -v64, v61, v60
	v_fma_f32 v67, -v65, v61, v60
	v_cmp_ge_f32_e64 s[0:1], 0, v66
	s_nop 1
	v_cndmask_b32_e64 v61, v61, v64, s[0:1]
	v_cmp_lt_f32_e64 s[0:1], 0, v67
	s_nop 1
	v_cndmask_b32_e64 v61, v61, v65, s[0:1]
	v_mul_f32_e32 v64, 0x37800000, v61
	v_cndmask_b32_e32 v61, v61, v64, vcc
	v_cmp_class_f32_e32 vcc, v60, v59
	s_nop 1
	v_cndmask_b32_e32 v60, v61, v60, vcc
	v_div_scale_f32 v61, s[0:1], v60, v60, 1.0
	v_rcp_f32_e32 v65, v61
	v_div_scale_f32 v64, vcc, 1.0, v60, 1.0
	v_fma_f32 v66, -v61, v65, 1.0
	v_fmac_f32_e32 v65, v66, v65
	v_mul_f32_e32 v66, v64, v65
	v_fma_f32 v67, -v61, v66, v64
	v_fmac_f32_e32 v66, v67, v65
	v_fma_f32 v61, -v61, v66, v64
	v_div_fmas_f32 v61, v61, v65, v66
	v_div_fixup_f32 v60, v61, v60, 1.0
	v_pk_mul_f32 v[64:65], v[60:61], v[96:97] op_sel_hi:[0,1]
	v_pk_mul_f32 v[66:67], v[60:61], v[98:99] op_sel_hi:[0,1]
	v_pk_mul_f32 v[62:63], v[60:61], v[62:63] op_sel_hi:[0,1]
	v_pk_mul_f32 v[46:47], v[60:61], v[46:47] op_sel_hi:[0,1]
	v_pk_mul_f32 v[70:71], v[60:61], v[100:101] op_sel_hi:[0,1]
	v_pk_mul_f32 v[40:41], v[60:61], v[40:41] op_sel_hi:[0,1]
	v_pk_mul_f32 v[44:45], v[60:61], v[44:45] op_sel_hi:[0,1]
	v_pk_mul_f32 v[76:77], v[60:61], v[42:43] op_sel_hi:[0,1]
	v_pk_mul_f32 v[68:69], v[60:61], v[68:69] op_sel_hi:[0,1]
	v_pk_mul_f32 v[78:79], v[60:61], v[36:37] op_sel_hi:[0,1]
	v_pk_mul_f32 v[80:81], v[60:61], v[102:103] op_sel_hi:[0,1]
	v_pk_mul_f32 v[82:83], v[60:61], v[38:39] op_sel_hi:[0,1]
	v_pk_mul_f32 v[72:73], v[60:61], v[72:73] op_sel_hi:[0,1]
	v_pk_mul_f32 v[74:75], v[60:61], v[74:75] op_sel_hi:[0,1]
	v_pk_mul_f32 v[84:85], v[60:61], v[32:33] op_sel_hi:[0,1]
	v_pk_mul_f32 v[86:87], v[60:61], v[34:35] op_sel_hi:[0,1]
	v_pk_mul_f32 v[34:35], v[6:7], v[66:67]
	v_pk_mul_f32 v[32:33], v[4:5], v[64:65]
	v_pk_mul_f32 v[38:39], v[2:3], v[46:47]
	v_pk_mul_f32 v[36:37], v[0:1], v[62:63]
	v_pk_mul_f32 v[42:43], v[14:15], v[40:41]
	v_pk_mul_f32 v[40:41], v[12:13], v[70:71]
	v_pk_mul_f32 v[46:47], v[10:11], v[76:77]
	v_pk_mul_f32 v[44:45], v[8:9], v[44:45]
	v_pk_mul_f32 v[62:63], v[18:19], v[78:79]
	v_pk_mul_f32 v[60:61], v[16:17], v[68:69]
	v_pk_mul_f32 v[66:67], v[22:23], v[82:83]
	v_pk_mul_f32 v[64:65], v[20:21], v[80:81]
	v_pk_mul_f32 v[70:71], v[26:27], v[74:75]
	v_pk_mul_f32 v[68:69], v[24:25], v[72:73]
	v_pk_mul_f32 v[74:75], v[30:31], v[86:87]
	v_pk_mul_f32 v[72:73], v[28:29], v[84:85]
	global_store_dwordx4 v[50:51], v[32:35], off offset:-4096
	global_store_dwordx4 v[50:51], v[36:39], off offset:-4080
	global_store_dwordx4 v[50:51], v[40:43], off offset:-2048
	global_store_dwordx4 v[50:51], v[44:47], off offset:-2032
	global_store_dwordx4 v[50:51], v[60:63], off
	global_store_dwordx4 v[50:51], v[64:67], off offset:16
	global_store_dwordx4 v[50:51], v[68:71], off offset:2048
	global_store_dwordx4 v[50:51], v[72:75], off offset:2064
	v_lshl_add_u64 v[50:51], v[50:51], 0, s[6:7]
	s_cbranch_scc1 .LBB0_1544
